# speedup vs baseline: 1.0183x; 1.0183x over previous
; template <bool WIDE>
; __device__ __forceinline__ void outproj_tile(const Params& P, int l, int mt, int nt, char* smem) {
;     ...
; #pragma unroll 4
;     for (int q = 0; q < 16; ++q) {
;       float4 y = *(const float4*)(cs + r * CSTR + half * 64 + q * 4);
;       float4 xv = *(const float4*)(xin + q * 4);
;       float4 g = *(const float4*)(g1 + q * 4);
;       float4 o = make_float4(xv.x + g.x * y.x, xv.y + g.y * y.y, xv.z + g.z * y.z, xv.w + g.w * y.w);
;       *(float4*)(xo + q * 4) = o;
;     }
.LBB0_716:
	v_lshl_add_u64 v[144:145], v[138:139], 0, s[18:19]
	v_add_co_u32_e32 v160, vcc, 0x11f42000, v144
	v_lshl_add_u64 v[148:149], v[132:133], 0, s[18:19]
	s_nop 0
	v_addc_co_u32_e32 v161, vcc, 0, v145, vcc
	global_load_dwordx4 v[140:143], v[148:149], off
	global_load_dwordx4 v[144:147], v[160:161], off
	global_load_dwordx4 v[164:167], v[148:149], off offset:16
	global_load_dwordx4 v[168:171], v[160:161], off offset:16
	global_load_dwordx4 v[172:175], v[148:149], off offset:32
	global_load_dwordx4 v[176:179], v[160:161], off offset:32
	global_load_dwordx4 v[180:183], v[148:149], off offset:48
	global_load_dwordx4 v[184:187], v[160:161], off offset:48
	ds_read_b128 v[152:155], v130
	ds_read_b128 v[156:159], v130 offset:16
	ds_read_b128 v[188:191], v130 offset:32
	ds_read_b128 v[192:195], v130 offset:48
	v_add_u32_e32 v130, 64, v130
	v_lshl_add_u64 v[162:163], v[136:137], 0, s[18:19]
	s_add_u32 s18, s18, 64
	s_addc_u32 s19, s19, 0
	s_cmpk_eq_i32 s18, 0x100
	s_waitcnt vmcnt(6) lgkmcnt(3)
	v_pk_fma_f32 v[140:141], v[152:153], v[144:145], v[140:141]
	v_pk_fma_f32 v[142:143], v[154:155], v[146:147], v[142:143]
	global_store_dwordx4 v[162:163], v[140:143], off
	s_waitcnt vmcnt(5) lgkmcnt(2)
	v_pk_fma_f32 v[164:165], v[156:157], v[168:169], v[164:165]
	v_pk_fma_f32 v[166:167], v[158:159], v[170:171], v[166:167]
	global_store_dwordx4 v[162:163], v[164:167], off offset:16
	s_waitcnt vmcnt(4) lgkmcnt(1)
	v_pk_fma_f32 v[172:173], v[188:189], v[176:177], v[172:173]
	v_pk_fma_f32 v[174:175], v[190:191], v[178:179], v[174:175]
	global_store_dwordx4 v[162:163], v[172:175], off offset:32
	s_waitcnt vmcnt(3) lgkmcnt(0)
	v_pk_fma_f32 v[180:181], v[192:193], v[184:185], v[180:181]
	v_pk_fma_f32 v[182:183], v[194:195], v[186:187], v[182:183]
	global_store_dwordx4 v[162:163], v[180:183], off offset:48
	s_cbranch_scc0 .LBB0_716
	s_mov_b32 s15, 1
	s_mov_b64 s[18:19], 0
	s_and_b64 vcc, exec, s[20:21]
	s_barrier
	s_cbranch_vccz .LBB0_709
	s_add_i32 s51, s51, s94
	s_cmpk_gt_i32 s51, 0x3ff
	s_cbranch_scc0 .LBB0_706

; template <bool WIDE>
; __device__ __forceinline__ void outproj_tile(const Params& P, int l, int mt, int nt, char* smem) {
;     ...
; #pragma unroll 4
;     for (int q = 0; q < 16; ++q) {
;       float4 y = *(const float4*)(cs + r * CSTR + half * 64 + q * 4);
;       float4 xv = *(const float4*)(xin + q * 4);
;       float4 g = *(const float4*)(g1 + q * 4);
;       float4 o = make_float4(xv.x + g.x * y.x, xv.y + g.y * y.y, xv.z + g.z * y.z, xv.w + g.w * y.w);
;       *(float4*)(xo + q * 4) = o;
;     }
.LBB0_1720:
	v_lshl_add_u64 v[148:149], v[138:139], 0, s[16:17]
	v_add_co_u32_e32 v162, vcc, s50, v148
	v_lshl_add_u64 v[160:161], v[132:133], 0, s[16:17]
	s_nop 0
	v_addc_co_u32_e32 v163, vcc, 0, v149, vcc
	global_load_dwordx4 v[144:147], v[160:161], off
	global_load_dwordx4 v[148:151], v[162:163], off
	global_load_dwordx4 v[140:143], v[160:161], off offset:16
	global_load_dwordx4 v[164:167], v[162:163], off offset:16
	global_load_dwordx4 v[168:171], v[160:161], off offset:32
	global_load_dwordx4 v[172:175], v[162:163], off offset:32
	global_load_dwordx4 v[176:179], v[160:161], off offset:48
	global_load_dwordx4 v[180:183], v[162:163], off offset:48
	ds_read_b128 v[152:155], v130
	ds_read_b128 v[156:159], v130 offset:16
	ds_read_b128 v[184:187], v130 offset:32
	ds_read_b128 v[188:191], v130 offset:48
	v_add_u32_e32 v130, 64, v130
	s_add_u32 s16, s16, 64
	s_addc_u32 s17, s17, 0
	s_cmpk_eq_i32 s16, 0x100
	s_waitcnt vmcnt(6) lgkmcnt(3)
	v_pk_fma_f32 v[144:145], v[152:153], v[148:149], v[144:145]
	v_pk_fma_f32 v[146:147], v[154:155], v[150:151], v[146:147]
	global_store_dwordx4 v[160:161], v[144:147], off
	s_waitcnt vmcnt(5) lgkmcnt(2)
	v_pk_fma_f32 v[140:141], v[156:157], v[164:165], v[140:141]
	v_pk_fma_f32 v[142:143], v[158:159], v[166:167], v[142:143]
	global_store_dwordx4 v[160:161], v[140:143], off offset:16
	s_waitcnt vmcnt(4) lgkmcnt(1)
	v_pk_fma_f32 v[168:169], v[184:185], v[172:173], v[168:169]
	v_pk_fma_f32 v[170:171], v[186:187], v[174:175], v[170:171]
	global_store_dwordx4 v[160:161], v[168:171], off offset:32
	s_waitcnt vmcnt(3) lgkmcnt(0)
	v_pk_fma_f32 v[176:177], v[188:189], v[180:181], v[176:177]
	v_pk_fma_f32 v[178:179], v[190:191], v[182:183], v[178:179]
	global_store_dwordx4 v[160:161], v[176:179], off offset:48
	s_cbranch_scc0 .LBB0_1720
	s_mov_b32 s53, 1
	s_mov_b64 s[16:17], 0
	s_and_b64 vcc, exec, s[14:15]
	s_barrier
	s_cbranch_vccz .LBB0_1717
	s_add_i32 s51, s51, s94
	s_cmpk_lt_i32 s51, 0x400
	s_cbranch_scc1 .LBB0_1714
